# v41 plus 64-byte alignment of the four GEMM inner-loop heads (code placement)
# speedup vs baseline: 1.0109x; 1.0039x over previous
; template <bool BF16, class Epi, class Sched, bool ALIGN_EPI = true, bool SP2 = true>
; __device__ __forceinline__ void gemm_phase(LAS unsigned char* lds, const Gemm g, const Sched& S, const Epi& E) {
;     ...
;         const bool has_next = S.next(ui + 1, nxt);
;         const char* nA = has_next ? (const char*)g.A + (size_t)nxt.pm * tstep : cA; const char* nB = has_next ? (const char*)g.Bt + (size_t)nxt.pn * tstep : cB;
;     ...
; #pragma unroll
;         for (int a = 0; a < 2; ++a)
; #pragma unroll
;             for (int b = 0; b < 2; ++b)
; #pragma unroll
;                 for (int m = 0; m < 4; ++m)
; #pragma unroll
;                     for (int n = 0; n < 2; ++n) acc[a][b][m][n] = (f32x4){0.f, 0.f, 0.f, 0.f};
.LBB0_266:
	s_ashr_i32 s23, s22, 31
	s_lshl_b64 s[28:29], s[22:23], 20
	s_add_u32 s28, s0, s28
	s_addc_u32 s29, s1, s29
	s_and_b64 s[30:31], s[4:5], exec
	s_cselect_b32 s23, s29, s35
	s_cselect_b32 s50, s28, s34
	s_ashr_i32 s21, s20, 31
	s_lshl_b64 s[30:31], s[20:21], 20
	s_add_u32 s30, s3, s30
	s_addc_u32 s31, s14, s31
	s_and_b64 s[38:39], s[4:5], exec
	s_cselect_b32 s21, s31, s37
	s_cselect_b32 s51, s30, s36
	s_add_u32 s34, s34, 0x80080
	s_addc_u32 s35, s35, 0
	s_add_u32 s52, s36, 0x100
	v_mov_b32_e32 v2, 0
	s_addc_u32 s53, s37, 0
	s_mov_b32 s54, -2
	v_mov_b32_e32 v3, v2
	v_mov_b32_e32 v4, v2
	v_mov_b32_e32 v5, v2
	v_mov_b32_e32 v6, v2
	v_mov_b32_e32 v7, v2
	v_mov_b32_e32 v8, v2
	v_mov_b32_e32 v9, v2
	v_mov_b32_e32 v10, v2
	v_mov_b32_e32 v11, v2
	v_mov_b32_e32 v12, v2
	v_mov_b32_e32 v13, v2
	v_mov_b32_e32 v14, v2
	v_mov_b32_e32 v15, v2
	v_mov_b32_e32 v16, v2
	v_mov_b32_e32 v17, v2
	v_mov_b32_e32 v26, v2
	v_mov_b32_e32 v27, v2
	v_mov_b32_e32 v28, v2
	v_mov_b32_e32 v29, v2
	v_mov_b32_e32 v30, v2
	v_mov_b32_e32 v31, v2
	v_mov_b32_e32 v32, v2
	v_mov_b32_e32 v33, v2
	v_mov_b32_e32 v42, v2
	v_mov_b32_e32 v43, v2
	v_mov_b32_e32 v44, v2
	v_mov_b32_e32 v45, v2
	v_mov_b32_e32 v46, v2
	v_mov_b32_e32 v47, v2
	v_mov_b32_e32 v48, v2
	v_mov_b32_e32 v49, v2
	v_mov_b32_e32 v18, v2
	v_mov_b32_e32 v19, v2
	v_mov_b32_e32 v20, v2
	v_mov_b32_e32 v21, v2
	v_mov_b32_e32 v22, v2
	v_mov_b32_e32 v23, v2
	v_mov_b32_e32 v24, v2
	v_mov_b32_e32 v25, v2
	v_mov_b32_e32 v34, v2
	v_mov_b32_e32 v35, v2
	v_mov_b32_e32 v36, v2
	v_mov_b32_e32 v37, v2
	v_mov_b32_e32 v38, v2
	v_mov_b32_e32 v39, v2
	v_mov_b32_e32 v40, v2
	v_mov_b32_e32 v41, v2
	v_mov_b32_e32 v50, v2
	v_mov_b32_e32 v51, v2
	v_mov_b32_e32 v52, v2
	v_mov_b32_e32 v53, v2
	v_mov_b32_e32 v54, v2
	v_mov_b32_e32 v55, v2
	v_mov_b32_e32 v56, v2
	v_mov_b32_e32 v57, v2
	v_mov_b32_e32 v58, v2
	v_mov_b32_e32 v59, v2
	v_mov_b32_e32 v60, v2
	v_mov_b32_e32 v61, v2
	v_mov_b32_e32 v62, v2
	v_mov_b32_e32 v63, v2
	v_mov_b32_e32 v64, v2
	v_mov_b32_e32 v65, v2
	v_mov_b32_e32 v66, v2
	v_mov_b32_e32 v67, v2
	v_mov_b32_e32 v68, v2
	v_mov_b32_e32 v69, v2
	v_mov_b32_e32 v70, v2
	v_mov_b32_e32 v71, v2
	v_mov_b32_e32 v72, v2
	v_mov_b32_e32 v73, v2
	v_mov_b32_e32 v74, v2
	v_mov_b32_e32 v75, v2
	v_mov_b32_e32 v76, v2
	v_mov_b32_e32 v77, v2
	v_mov_b32_e32 v78, v2
	v_mov_b32_e32 v79, v2
	v_mov_b32_e32 v80, v2
	v_mov_b32_e32 v81, v2
	v_mov_b32_e32 v90, v2
	v_mov_b32_e32 v91, v2
	v_mov_b32_e32 v92, v2
	v_mov_b32_e32 v93, v2
	v_mov_b32_e32 v94, v2
	v_mov_b32_e32 v95, v2
	v_mov_b32_e32 v96, v2
	v_mov_b32_e32 v97, v2
	v_mov_b32_e32 v106, v2
	v_mov_b32_e32 v107, v2
	v_mov_b32_e32 v108, v2
	v_mov_b32_e32 v109, v2
	v_mov_b32_e32 v110, v2
	v_mov_b32_e32 v111, v2
	v_mov_b32_e32 v112, v2
	v_mov_b32_e32 v113, v2
	v_mov_b32_e32 v82, v2
	v_mov_b32_e32 v83, v2
	v_mov_b32_e32 v84, v2
	v_mov_b32_e32 v85, v2
	v_mov_b32_e32 v86, v2
	v_mov_b32_e32 v87, v2
	v_mov_b32_e32 v88, v2
	v_mov_b32_e32 v89, v2
	v_mov_b32_e32 v98, v2
	v_mov_b32_e32 v99, v2
	v_mov_b32_e32 v100, v2
	v_mov_b32_e32 v101, v2
	v_mov_b32_e32 v102, v2
	v_mov_b32_e32 v103, v2
	v_mov_b32_e32 v104, v2
	v_mov_b32_e32 v105, v2
	v_mov_b32_e32 v114, v2
	v_mov_b32_e32 v115, v2
	v_mov_b32_e32 v116, v2
	v_mov_b32_e32 v117, v2
	v_mov_b32_e32 v118, v2
	v_mov_b32_e32 v119, v2
	v_mov_b32_e32 v120, v2
	v_mov_b32_e32 v121, v2
	v_mov_b32_e32 v122, v2
	v_mov_b32_e32 v123, v2
	v_mov_b32_e32 v124, v2
	v_mov_b32_e32 v125, v2
	v_mov_b32_e32 v126, v2
	v_mov_b32_e32 v127, v2
	v_mov_b32_e32 v128, v2
	v_mov_b32_e32 v129, v2
	.p2alignl 6, 3212836864

; template <bool BF16, class Epi, class Sched, bool ALIGN_EPI = true, bool SP2 = true>
; __device__ __forceinline__ void gemm_phase(LAS unsigned char* lds, const Gemm g, const Sched& S, const Epi& E) {
;     ...
;         const bool has_next = S.next(ui + 1, nxt);
;         const char* nA = has_next ? (const char*)g.A + (size_t)nxt.pm * tstep : cA; const char* nB = has_next ? (const char*)g.Bt + (size_t)nxt.pn * tstep : cB;
;     ...
; #pragma unroll
;         for (int a = 0; a < 2; ++a)
; #pragma unroll
;             for (int b = 0; b < 2; ++b)
; #pragma unroll
;                 for (int m = 0; m < 4; ++m)
; #pragma unroll
;                     for (int n = 0; n < 2; ++n) acc[a][b][m][n] = (f32x4){0.f, 0.f, 0.f, 0.f};
.LBB0_711:
	s_ashr_i32 s37, s36, 31
	s_lshl_b64 s[38:39], s[36:37], 20
	s_add_u32 s38, s1, s38
	s_addc_u32 s39, s3, s39
	s_and_b64 s[40:41], s[4:5], exec
	s_cselect_b32 s37, s39, s45
	s_cselect_b32 s60, s38, s44
	s_ashr_i32 s35, s34, 31
	s_lshl_b64 s[40:41], s[34:35], 20
	s_add_u32 s40, s14, s40
	s_addc_u32 s41, s15, s41
	s_and_b64 s[48:49], s[4:5], exec
	s_cselect_b32 s35, s41, s47
	s_cselect_b32 s61, s40, s46
	s_add_u32 s44, s44, 0x80080
	s_addc_u32 s45, s45, 0
	s_add_u32 s62, s46, 0x100
	v_mov_b32_e32 v2, 0
	s_addc_u32 s63, s47, 0
	s_mov_b32 s64, -2
	v_mov_b32_e32 v3, v2
	v_mov_b32_e32 v4, v2
	v_mov_b32_e32 v5, v2
	v_mov_b32_e32 v6, v2
	v_mov_b32_e32 v7, v2
	v_mov_b32_e32 v8, v2
	v_mov_b32_e32 v9, v2
	v_mov_b32_e32 v18, v2
	v_mov_b32_e32 v19, v2
	v_mov_b32_e32 v20, v2
	v_mov_b32_e32 v21, v2
	v_mov_b32_e32 v22, v2
	v_mov_b32_e32 v23, v2
	v_mov_b32_e32 v24, v2
	v_mov_b32_e32 v25, v2
	v_mov_b32_e32 v34, v2
	v_mov_b32_e32 v35, v2
	v_mov_b32_e32 v36, v2
	v_mov_b32_e32 v37, v2
	v_mov_b32_e32 v38, v2
	v_mov_b32_e32 v39, v2
	v_mov_b32_e32 v40, v2
	v_mov_b32_e32 v41, v2
	v_mov_b32_e32 v50, v2
	v_mov_b32_e32 v51, v2
	v_mov_b32_e32 v52, v2
	v_mov_b32_e32 v53, v2
	v_mov_b32_e32 v54, v2
	v_mov_b32_e32 v55, v2
	v_mov_b32_e32 v56, v2
	v_mov_b32_e32 v57, v2
	v_mov_b32_e32 v10, v2
	v_mov_b32_e32 v11, v2
	v_mov_b32_e32 v12, v2
	v_mov_b32_e32 v13, v2
	v_mov_b32_e32 v14, v2
	v_mov_b32_e32 v15, v2
	v_mov_b32_e32 v16, v2
	v_mov_b32_e32 v17, v2
	v_mov_b32_e32 v26, v2
	v_mov_b32_e32 v27, v2
	v_mov_b32_e32 v28, v2
	v_mov_b32_e32 v29, v2
	v_mov_b32_e32 v30, v2
	v_mov_b32_e32 v31, v2
	v_mov_b32_e32 v32, v2
	v_mov_b32_e32 v33, v2
	v_mov_b32_e32 v42, v2
	v_mov_b32_e32 v43, v2
	v_mov_b32_e32 v44, v2
	v_mov_b32_e32 v45, v2
	v_mov_b32_e32 v46, v2
	v_mov_b32_e32 v47, v2
	v_mov_b32_e32 v48, v2
	v_mov_b32_e32 v49, v2
	v_mov_b32_e32 v58, v2
	v_mov_b32_e32 v59, v2
	v_mov_b32_e32 v60, v2
	v_mov_b32_e32 v61, v2
	v_mov_b32_e32 v62, v2
	v_mov_b32_e32 v63, v2
	v_mov_b32_e32 v64, v2
	v_mov_b32_e32 v65, v2
	v_mov_b32_e32 v66, v2
	v_mov_b32_e32 v67, v2
	v_mov_b32_e32 v68, v2
	v_mov_b32_e32 v69, v2
	v_mov_b32_e32 v70, v2
	v_mov_b32_e32 v71, v2
	v_mov_b32_e32 v72, v2
	v_mov_b32_e32 v73, v2
	v_mov_b32_e32 v82, v2
	v_mov_b32_e32 v83, v2
	v_mov_b32_e32 v84, v2
	v_mov_b32_e32 v85, v2
	v_mov_b32_e32 v86, v2
	v_mov_b32_e32 v87, v2
	v_mov_b32_e32 v88, v2
	v_mov_b32_e32 v89, v2
	v_mov_b32_e32 v98, v2
	v_mov_b32_e32 v99, v2
	v_mov_b32_e32 v100, v2
	v_mov_b32_e32 v101, v2
	v_mov_b32_e32 v102, v2
	v_mov_b32_e32 v103, v2
	v_mov_b32_e32 v104, v2
	v_mov_b32_e32 v105, v2
	v_mov_b32_e32 v114, v2
	v_mov_b32_e32 v115, v2
	v_mov_b32_e32 v116, v2
	v_mov_b32_e32 v117, v2
	v_mov_b32_e32 v118, v2
	v_mov_b32_e32 v119, v2
	v_mov_b32_e32 v120, v2
	v_mov_b32_e32 v121, v2
	v_mov_b32_e32 v74, v2
	v_mov_b32_e32 v75, v2
	v_mov_b32_e32 v76, v2
	v_mov_b32_e32 v77, v2
	v_mov_b32_e32 v78, v2
	v_mov_b32_e32 v79, v2
	v_mov_b32_e32 v80, v2
	v_mov_b32_e32 v81, v2
	v_mov_b32_e32 v90, v2
	v_mov_b32_e32 v91, v2
	v_mov_b32_e32 v92, v2
	v_mov_b32_e32 v93, v2
	v_mov_b32_e32 v94, v2
	v_mov_b32_e32 v95, v2
	v_mov_b32_e32 v96, v2
	v_mov_b32_e32 v97, v2
	v_mov_b32_e32 v106, v2
	v_mov_b32_e32 v107, v2
	v_mov_b32_e32 v108, v2
	v_mov_b32_e32 v109, v2
	v_mov_b32_e32 v110, v2
	v_mov_b32_e32 v111, v2
	v_mov_b32_e32 v112, v2
	v_mov_b32_e32 v113, v2
	v_mov_b32_e32 v122, v2
	v_mov_b32_e32 v123, v2
	v_mov_b32_e32 v124, v2
	v_mov_b32_e32 v125, v2
	v_mov_b32_e32 v126, v2
	v_mov_b32_e32 v127, v2
	v_mov_b32_e32 v128, v2
	v_mov_b32_e32 v129, v2
	.p2alignl 6, 3212836864

; template <bool BF16, class Epi, class Sched, bool ALIGN_EPI = true, bool SP2 = true>
; __device__ __forceinline__ void gemm_phase(LAS unsigned char* lds, const Gemm g, const Sched& S, const Epi& E) {
;     ...
;         const bool has_next = S.next(ui + 1, nxt);
;         const char* nA = has_next ? (const char*)g.A + (size_t)nxt.pm * tstep : cA; const char* nB = has_next ? (const char*)g.Bt + (size_t)nxt.pn * tstep : cB;
;     ...
; #pragma unroll
;         for (int a = 0; a < 2; ++a)
; #pragma unroll
;             for (int b = 0; b < 2; ++b)
; #pragma unroll
;                 for (int m = 0; m < 4; ++m)
; #pragma unroll
;                     for (int n = 0; n < 2; ++n) acc[a][b][m][n] = (f32x4){0.f, 0.f, 0.f, 0.f};
.LBB0_868:
	s_ashr_i32 s31, s30, 31
	s_lshl_b64 s[34:35], s[30:31], 20
	s_add_u32 s34, s1, s34
	s_addc_u32 s35, s3, s35
	s_and_b64 s[36:37], s[4:5], exec
	s_cselect_b32 s31, s35, s41
	s_cselect_b32 s60, s34, s40
	s_ashr_i32 s29, s28, 31
	s_lshl_b64 s[36:37], s[28:29], 20
	s_add_u32 s36, s14, s36
	s_addc_u32 s37, s15, s37
	s_and_b64 s[44:45], s[4:5], exec
	s_cselect_b32 s29, s37, s43
	s_cselect_b32 s61, s36, s42
	s_add_u32 s40, s40, 0x80080
	s_addc_u32 s41, s41, 0
	s_add_u32 s62, s42, 0x100
	v_mov_b32_e32 v2, 0
	s_addc_u32 s63, s43, 0
	s_mov_b32 s64, -2
	v_mov_b32_e32 v3, v2
	v_mov_b32_e32 v4, v2
	v_mov_b32_e32 v5, v2
	v_mov_b32_e32 v6, v2
	v_mov_b32_e32 v7, v2
	v_mov_b32_e32 v8, v2
	v_mov_b32_e32 v9, v2
	v_mov_b32_e32 v18, v2
	v_mov_b32_e32 v19, v2
	v_mov_b32_e32 v20, v2
	v_mov_b32_e32 v21, v2
	v_mov_b32_e32 v22, v2
	v_mov_b32_e32 v23, v2
	v_mov_b32_e32 v24, v2
	v_mov_b32_e32 v25, v2
	v_mov_b32_e32 v34, v2
	v_mov_b32_e32 v35, v2
	v_mov_b32_e32 v36, v2
	v_mov_b32_e32 v37, v2
	v_mov_b32_e32 v38, v2
	v_mov_b32_e32 v39, v2
	v_mov_b32_e32 v40, v2
	v_mov_b32_e32 v41, v2
	v_mov_b32_e32 v50, v2
	v_mov_b32_e32 v51, v2
	v_mov_b32_e32 v52, v2
	v_mov_b32_e32 v53, v2
	v_mov_b32_e32 v54, v2
	v_mov_b32_e32 v55, v2
	v_mov_b32_e32 v56, v2
	v_mov_b32_e32 v57, v2
	v_mov_b32_e32 v10, v2
	v_mov_b32_e32 v11, v2
	v_mov_b32_e32 v12, v2
	v_mov_b32_e32 v13, v2
	v_mov_b32_e32 v14, v2
	v_mov_b32_e32 v15, v2
	v_mov_b32_e32 v16, v2
	v_mov_b32_e32 v17, v2
	v_mov_b32_e32 v26, v2
	v_mov_b32_e32 v27, v2
	v_mov_b32_e32 v28, v2
	v_mov_b32_e32 v29, v2
	v_mov_b32_e32 v30, v2
	v_mov_b32_e32 v31, v2
	v_mov_b32_e32 v32, v2
	v_mov_b32_e32 v33, v2
	v_mov_b32_e32 v42, v2
	v_mov_b32_e32 v43, v2
	v_mov_b32_e32 v44, v2
	v_mov_b32_e32 v45, v2
	v_mov_b32_e32 v46, v2
	v_mov_b32_e32 v47, v2
	v_mov_b32_e32 v48, v2
	v_mov_b32_e32 v49, v2
	v_mov_b32_e32 v58, v2
	v_mov_b32_e32 v59, v2
	v_mov_b32_e32 v60, v2
	v_mov_b32_e32 v61, v2
	v_mov_b32_e32 v62, v2
	v_mov_b32_e32 v63, v2
	v_mov_b32_e32 v64, v2
	v_mov_b32_e32 v65, v2
	v_mov_b32_e32 v66, v2
	v_mov_b32_e32 v67, v2
	v_mov_b32_e32 v68, v2
	v_mov_b32_e32 v69, v2
	v_mov_b32_e32 v70, v2
	v_mov_b32_e32 v71, v2
	v_mov_b32_e32 v72, v2
	v_mov_b32_e32 v73, v2
	v_mov_b32_e32 v82, v2
	v_mov_b32_e32 v83, v2
	v_mov_b32_e32 v84, v2
	v_mov_b32_e32 v85, v2
	v_mov_b32_e32 v86, v2
	v_mov_b32_e32 v87, v2
	v_mov_b32_e32 v88, v2
	v_mov_b32_e32 v89, v2
	v_mov_b32_e32 v98, v2
	v_mov_b32_e32 v99, v2
	v_mov_b32_e32 v100, v2
	v_mov_b32_e32 v101, v2
	v_mov_b32_e32 v102, v2
	v_mov_b32_e32 v103, v2
	v_mov_b32_e32 v104, v2
	v_mov_b32_e32 v105, v2
	v_mov_b32_e32 v114, v2
	v_mov_b32_e32 v115, v2
	v_mov_b32_e32 v116, v2
	v_mov_b32_e32 v117, v2
	v_mov_b32_e32 v118, v2
	v_mov_b32_e32 v119, v2
	v_mov_b32_e32 v120, v2
	v_mov_b32_e32 v121, v2
	v_mov_b32_e32 v74, v2
	v_mov_b32_e32 v75, v2
	v_mov_b32_e32 v76, v2
	v_mov_b32_e32 v77, v2
	v_mov_b32_e32 v78, v2
	v_mov_b32_e32 v79, v2
	v_mov_b32_e32 v80, v2
	v_mov_b32_e32 v81, v2
	v_mov_b32_e32 v90, v2
	v_mov_b32_e32 v91, v2
	v_mov_b32_e32 v92, v2
	v_mov_b32_e32 v93, v2
	v_mov_b32_e32 v94, v2
	v_mov_b32_e32 v95, v2
	v_mov_b32_e32 v96, v2
	v_mov_b32_e32 v97, v2
	v_mov_b32_e32 v106, v2
	v_mov_b32_e32 v107, v2
	v_mov_b32_e32 v108, v2
	v_mov_b32_e32 v109, v2
	v_mov_b32_e32 v110, v2
	v_mov_b32_e32 v111, v2
	v_mov_b32_e32 v112, v2
	v_mov_b32_e32 v113, v2
	v_mov_b32_e32 v122, v2
	v_mov_b32_e32 v123, v2
	v_mov_b32_e32 v124, v2
	v_mov_b32_e32 v125, v2
	v_mov_b32_e32 v126, v2
	v_mov_b32_e32 v127, v2
	v_mov_b32_e32 v128, v2
	v_mov_b32_e32 v129, v2
	.p2alignl 6, 3212836864

; template <bool BF16, class Epi, class Sched, bool ALIGN_EPI = true, bool SP2 = true>
; __device__ __forceinline__ void gemm_phase(LAS unsigned char* lds, const Gemm g, const Sched& S, const Epi& E) {
;     ...
;         const bool has_next = S.next(ui + 1, nxt);
;         const char* nA = has_next ? (const char*)g.A + (size_t)nxt.pm * tstep : cA; const char* nB = has_next ? (const char*)g.Bt + (size_t)nxt.pn * tstep : cB;
;     ...
; #pragma unroll
;         for (int a = 0; a < 2; ++a)
; #pragma unroll
;             for (int b = 0; b < 2; ++b)
; #pragma unroll
;                 for (int m = 0; m < 4; ++m)
; #pragma unroll
;                     for (int n = 0; n < 2; ++n) acc[a][b][m][n] = (f32x4){0.f, 0.f, 0.f, 0.f};
.LBB0_957:
	s_ashr_i32 s31, s30, 31
	s_lshl_b64 s[34:35], s[30:31], 22
	s_add_u32 s34, s1, s34
	s_addc_u32 s35, s3, s35
	s_and_b64 s[36:37], s[4:5], exec
	s_cselect_b32 s31, s35, s41
	s_cselect_b32 s62, s34, s40
	s_ashr_i32 s29, s28, 31
	s_lshl_b64 s[36:37], s[28:29], 22
	s_add_u32 s36, s14, s36
	s_addc_u32 s37, s15, s37
	s_and_b64 s[44:45], s[4:5], exec
	s_cselect_b32 s29, s37, s43
	s_cselect_b32 s63, s36, s42
	s_add_u32 s40, s40, 0x200080
	s_addc_u32 s41, s41, 0
	s_add_u32 s64, s42, 0x100
	v_mov_b32_e32 v2, 0
	s_addc_u32 s65, s43, 0
	s_mov_b32 s66, -2
	v_mov_b32_e32 v3, v2
	v_mov_b32_e32 v4, v2
	v_mov_b32_e32 v5, v2
	v_mov_b32_e32 v6, v2
	v_mov_b32_e32 v7, v2
	v_mov_b32_e32 v8, v2
	v_mov_b32_e32 v9, v2
	v_mov_b32_e32 v10, v2
	v_mov_b32_e32 v11, v2
	v_mov_b32_e32 v12, v2
	v_mov_b32_e32 v13, v2
	v_mov_b32_e32 v14, v2
	v_mov_b32_e32 v15, v2
	v_mov_b32_e32 v16, v2
	v_mov_b32_e32 v17, v2
	v_mov_b32_e32 v26, v2
	v_mov_b32_e32 v27, v2
	v_mov_b32_e32 v28, v2
	v_mov_b32_e32 v29, v2
	v_mov_b32_e32 v30, v2
	v_mov_b32_e32 v31, v2
	v_mov_b32_e32 v32, v2
	v_mov_b32_e32 v33, v2
	v_mov_b32_e32 v50, v2
	v_mov_b32_e32 v51, v2
	v_mov_b32_e32 v52, v2
	v_mov_b32_e32 v53, v2
	v_mov_b32_e32 v54, v2
	v_mov_b32_e32 v55, v2
	v_mov_b32_e32 v56, v2
	v_mov_b32_e32 v57, v2
	v_mov_b32_e32 v18, v2
	v_mov_b32_e32 v19, v2
	v_mov_b32_e32 v20, v2
	v_mov_b32_e32 v21, v2
	v_mov_b32_e32 v22, v2
	v_mov_b32_e32 v23, v2
	v_mov_b32_e32 v24, v2
	v_mov_b32_e32 v25, v2
	v_mov_b32_e32 v34, v2
	v_mov_b32_e32 v35, v2
	v_mov_b32_e32 v36, v2
	v_mov_b32_e32 v37, v2
	v_mov_b32_e32 v38, v2
	v_mov_b32_e32 v39, v2
	v_mov_b32_e32 v40, v2
	v_mov_b32_e32 v41, v2
	v_mov_b32_e32 v42, v2
	v_mov_b32_e32 v43, v2
	v_mov_b32_e32 v44, v2
	v_mov_b32_e32 v45, v2
	v_mov_b32_e32 v46, v2
	v_mov_b32_e32 v47, v2
	v_mov_b32_e32 v48, v2
	v_mov_b32_e32 v49, v2
	v_mov_b32_e32 v58, v2
	v_mov_b32_e32 v59, v2
	v_mov_b32_e32 v60, v2
	v_mov_b32_e32 v61, v2
	v_mov_b32_e32 v62, v2
	v_mov_b32_e32 v63, v2
	v_mov_b32_e32 v64, v2
	v_mov_b32_e32 v65, v2
	v_mov_b32_e32 v66, v2
	v_mov_b32_e32 v67, v2
	v_mov_b32_e32 v68, v2
	v_mov_b32_e32 v69, v2
	v_mov_b32_e32 v70, v2
	v_mov_b32_e32 v71, v2
	v_mov_b32_e32 v72, v2
	v_mov_b32_e32 v73, v2
	v_mov_b32_e32 v82, v2
	v_mov_b32_e32 v83, v2
	v_mov_b32_e32 v84, v2
	v_mov_b32_e32 v85, v2
	v_mov_b32_e32 v86, v2
	v_mov_b32_e32 v87, v2
	v_mov_b32_e32 v88, v2
	v_mov_b32_e32 v89, v2
	v_mov_b32_e32 v98, v2
	v_mov_b32_e32 v99, v2
	v_mov_b32_e32 v100, v2
	v_mov_b32_e32 v101, v2
	v_mov_b32_e32 v102, v2
	v_mov_b32_e32 v103, v2
	v_mov_b32_e32 v104, v2
	v_mov_b32_e32 v105, v2
	v_mov_b32_e32 v106, v2
	v_mov_b32_e32 v107, v2
	v_mov_b32_e32 v108, v2
	v_mov_b32_e32 v109, v2
	v_mov_b32_e32 v110, v2
	v_mov_b32_e32 v111, v2
	v_mov_b32_e32 v112, v2
	v_mov_b32_e32 v113, v2
	v_mov_b32_e32 v74, v2
	v_mov_b32_e32 v75, v2
	v_mov_b32_e32 v76, v2
	v_mov_b32_e32 v77, v2
	v_mov_b32_e32 v78, v2
	v_mov_b32_e32 v79, v2
	v_mov_b32_e32 v80, v2
	v_mov_b32_e32 v81, v2
	v_mov_b32_e32 v90, v2
	v_mov_b32_e32 v91, v2
	v_mov_b32_e32 v92, v2
	v_mov_b32_e32 v93, v2
	v_mov_b32_e32 v94, v2
	v_mov_b32_e32 v95, v2
	v_mov_b32_e32 v96, v2
	v_mov_b32_e32 v97, v2
	v_mov_b32_e32 v114, v2
	v_mov_b32_e32 v115, v2
	v_mov_b32_e32 v116, v2
	v_mov_b32_e32 v117, v2
	v_mov_b32_e32 v118, v2
	v_mov_b32_e32 v119, v2
	v_mov_b32_e32 v120, v2
	v_mov_b32_e32 v121, v2
	v_mov_b32_e32 v122, v2
	v_mov_b32_e32 v123, v2
	v_mov_b32_e32 v124, v2
	v_mov_b32_e32 v125, v2
	v_mov_b32_e32 v126, v2
	v_mov_b32_e32 v127, v2
	v_mov_b32_e32 v128, v2
	v_mov_b32_e32 v129, v2
	.p2alignl 6, 3212836864
